# gelu blocks of the in-projection epilogue re-emitted with packed f32 math x*rcp(1+exp2(x*(k0+k1*x*x)))
# speedup vs baseline: 1.0169x; 1.0065x over previous
;     __device__ __forceinline__ void operator()(const f32x4 (&acc)[2][2][4][2], const pg8::Unit& u, int wr, int wc, int fr, int fq) const {
;         const int row0 = u.pm * 256 + wr * 64 + fr, col0 = u.pn * 256 + wc * 32 + 8 * fq;
;         const bool do_gelu = u.pn < gelu_tiles, do_stat = u.pn >= stat_tile0;
;         f32x4 bv[2][2];
; #pragma unroll
;         for (int bj = 0; bj < 2; ++bj)
; #pragma unroll
;             for (int n = 0; n < 2; ++n) bv[bj][n] = bias ? *(const f32x4*)(bias + col0 + bj * 128 + 4 * n) : (f32x4){0.f, 0.f, 0.f, 0.f};
.LBB0_240:
	v_and_b32_e32 v238, 63, v163
	v_and_b32_e32 v239, 3, v238
	v_lshrrev_b32_e32 v238, 2, v238
	v_lshl_add_u32 v238, v239, 4, v238
	v_lshlrev_b32_e32 v238, 2, v238
	s_mov_b32 s98, 0xbdd2d3e7
	s_mov_b32 s100, 0xc0135761
	v_lshl_or_b32 v156, s78, 8, v166
	v_ashrrev_i32_e32 v157, 31, v156
	v_cndmask_b32_e64 v24, 0, 1, s[84:85]
	v_lshl_add_u64 v[158:159], v[156:157], 2, s[22:23]
	v_mov_b32_e32 v40, 0
	v_cmp_ne_u32_e64 s[12:13], 1, v24
	s_andn2_b64 vcc, exec, s[84:85]
	v_mov_b32_e32 v44, 0
	v_mov_b32_e32 v45, 0
	v_mov_b32_e32 v46, 0
	v_mov_b32_e32 v47, 0
	s_cbranch_vccnz .LBB0_242
	global_load_dwordx4 v[44:47], v[158:159], off

; __device__ __forceinline__ unsigned pk2(float lo, float hi) { return pg8::cvt_pk_bf16(lo, hi); }
; __device__ __forceinline__ float gelu_tanh(float x) { const float u = 1.5957691216057308f * (x + 0.044715f * x * x * x); return x * sigmoidf_(u); }
;     __device__ __forceinline__ void operator()(const f32x4 (&acc)[2][2][4][2], const pg8::Unit& u, int wr, int wc, int fr, int fq) const {
;     ...
;         for (int ai = 0; ai < 2; ++ai)
; #pragma unroll
;             for (int m = 0; m < 4; ++m) {
;                 const int row = row0 + ai * 128 + m * 16;
;                 bf16_t* rowp = O + (size_t)row * ldc + col0;
;                 float s = 0.f, ss = 0.f;
; #pragma unroll
;                 for (int bj = 0; bj < 2; ++bj) {
;                     f32x4 v0 = acc[ai][bj][m][0] + bv[bj][0], v1 = acc[ai][bj][m][1] + bv[bj][1];
;                     if (do_gelu) {
; #pragma unroll
;                         for (int e = 0; e < 4; ++e) { v0[e] = gelu_tanh(v0[e]); v1[e] = gelu_tanh(v1[e]); }
;                     }
; #pragma unroll
;                     for (int e = 0; e < 4; ++e) { s += v0[e] + v1[e]; ss += v0[e] * v0[e] + v1[e] * v1[e]; }
;                     u32x4 w; w.x = pk2(v0[0], v0[1]); w.y = pk2(v0[2], v0[3]); w.z = pk2(v1[0], v1[1]); w.w = pk2(v1[2], v1[3]);
;                     *(u32x4*)(rowp + bj * 128) = w;
.LBB0_248:
	s_cmp_lt_i32 s78, s37
	s_cselect_b64 s[94:95], -1, 0
	s_cmp_ge_i32 s78, s37
	s_waitcnt vmcnt(0)
	v_pk_add_f32 v[142:143], v[142:143], v[46:47]
	v_pk_add_f32 v[140:141], v[140:141], v[44:45]
	v_pk_add_f32 v[138:139], v[138:139], v[42:43]
	v_pk_add_f32 v[158:159], v[136:137], v[40:41]
	s_cbranch_scc1 .LBB0_250
	v_pk_mul_f32 v[136:137], v[140:141], v[140:141]
	v_pk_mul_f32 v[160:161], v[158:159], v[158:159]
	v_pk_mul_f32 v[174:175], v[142:143], v[142:143]
	v_pk_mul_f32 v[188:189], v[138:139], v[138:139]
	v_pk_mul_f32 v[136:137], v[136:137], s[98:99] op_sel_hi:[1,0]
	v_pk_mul_f32 v[160:161], v[160:161], s[98:99] op_sel_hi:[1,0]
	v_pk_mul_f32 v[174:175], v[174:175], s[98:99] op_sel_hi:[1,0]
	v_pk_mul_f32 v[188:189], v[188:189], s[98:99] op_sel_hi:[1,0]
	v_pk_add_f32 v[136:137], v[136:137], s[100:101] op_sel_hi:[1,0]
	v_pk_add_f32 v[160:161], v[160:161], s[100:101] op_sel_hi:[1,0]
	v_pk_add_f32 v[174:175], v[174:175], s[100:101] op_sel_hi:[1,0]
	v_pk_add_f32 v[188:189], v[188:189], s[100:101] op_sel_hi:[1,0]
	v_pk_mul_f32 v[136:137], v[136:137], v[140:141]
	v_pk_mul_f32 v[160:161], v[160:161], v[158:159]
	v_pk_mul_f32 v[174:175], v[174:175], v[142:143]
	v_pk_mul_f32 v[188:189], v[188:189], v[138:139]
	v_exp_f32_e32 v136, v136
	v_exp_f32_e32 v137, v137
	v_exp_f32_e32 v160, v160
	v_exp_f32_e32 v161, v161
	v_exp_f32_e32 v174, v174
	v_exp_f32_e32 v175, v175
	v_exp_f32_e32 v188, v188
	v_exp_f32_e32 v189, v189
	v_pk_add_f32 v[136:137], v[136:137], 1.0 op_sel_hi:[1,0]
	v_pk_add_f32 v[160:161], v[160:161], 1.0 op_sel_hi:[1,0]
	v_pk_add_f32 v[174:175], v[174:175], 1.0 op_sel_hi:[1,0]
	v_pk_add_f32 v[188:189], v[188:189], 1.0 op_sel_hi:[1,0]
	v_rcp_f32_e32 v136, v136
	v_rcp_f32_e32 v137, v137
	v_rcp_f32_e32 v160, v160
	v_rcp_f32_e32 v161, v161
	v_rcp_f32_e32 v174, v174
	v_rcp_f32_e32 v175, v175
	v_rcp_f32_e32 v188, v188
	v_rcp_f32_e32 v189, v189
	v_pk_mul_f32 v[140:141], v[140:141], v[136:137]
	v_pk_mul_f32 v[158:159], v[158:159], v[160:161]
	v_pk_mul_f32 v[142:143], v[142:143], v[174:175]
	v_pk_mul_f32 v[138:139], v[138:139], v[188:189]
.LBB0_250:
	v_lshl_add_u32 v136, s14, 8, v162
	v_mad_i64_i32 v[160:161], s[12:13], v136, s31, 0
	v_lshl_add_u64 v[160:161], v[160:161], 1, s[58:59]
	v_cndmask_b32_e64 v137, 0, 1, s[94:95]
	v_lshl_add_u64 v[160:161], v[156:157], 1, v[160:161]
	v_pk_add_f32 v[134:135], v[134:135], v[30:31]
	v_pk_add_f32 v[132:133], v[132:133], v[28:29]
	v_pk_add_f32 v[130:131], v[130:131], v[26:27]
	v_cmp_ne_u32_e64 s[12:13], 1, v137
	s_andn2_b64 vcc, exec, s[94:95]
	v_pk_add_f32 v[128:129], v[128:129], v[24:25]
	v_cvt_pk_bf16_f32 v188, v140, v141
	v_cvt_pk_bf16_f32 v189, v142, v143
	v_cvt_pk_bf16_f32 v190, v158, v159
	v_cvt_pk_bf16_f32 v191, v138, v139
	ds_bpermute_b32 v240, v238, v160
	ds_bpermute_b32 v241, v238, v161
	ds_bpermute_b32 v242, v238, v188
	ds_bpermute_b32 v243, v238, v189
	ds_bpermute_b32 v244, v238, v190
	ds_bpermute_b32 v245, v238, v191
	s_cbranch_vccnz .LBB0_252
	v_pk_mul_f32 v[174:175], v[132:133], v[132:133]
	v_pk_mul_f32 v[188:189], v[128:129], v[128:129]
	v_pk_mul_f32 v[190:191], v[134:135], v[134:135]
	v_pk_mul_f32 v[192:193], v[130:131], v[130:131]
	v_pk_mul_f32 v[174:175], v[174:175], s[98:99] op_sel_hi:[1,0]
	v_pk_mul_f32 v[188:189], v[188:189], s[98:99] op_sel_hi:[1,0]
	v_pk_mul_f32 v[190:191], v[190:191], s[98:99] op_sel_hi:[1,0]
	v_pk_mul_f32 v[192:193], v[192:193], s[98:99] op_sel_hi:[1,0]
	v_pk_add_f32 v[174:175], v[174:175], s[100:101] op_sel_hi:[1,0]
	v_pk_add_f32 v[188:189], v[188:189], s[100:101] op_sel_hi:[1,0]
	v_pk_add_f32 v[190:191], v[190:191], s[100:101] op_sel_hi:[1,0]
	v_pk_add_f32 v[192:193], v[192:193], s[100:101] op_sel_hi:[1,0]
	v_pk_mul_f32 v[174:175], v[174:175], v[132:133]
	v_pk_mul_f32 v[188:189], v[188:189], v[128:129]
	v_pk_mul_f32 v[190:191], v[190:191], v[134:135]
	v_pk_mul_f32 v[192:193], v[192:193], v[130:131]
	v_exp_f32_e32 v174, v174
	v_exp_f32_e32 v175, v175
	v_exp_f32_e32 v188, v188
	v_exp_f32_e32 v189, v189
	v_exp_f32_e32 v190, v190
	v_exp_f32_e32 v191, v191
	v_exp_f32_e32 v192, v192
	v_exp_f32_e32 v193, v193
	v_pk_add_f32 v[174:175], v[174:175], 1.0 op_sel_hi:[1,0]
	v_pk_add_f32 v[188:189], v[188:189], 1.0 op_sel_hi:[1,0]
	v_pk_add_f32 v[190:191], v[190:191], 1.0 op_sel_hi:[1,0]
	v_pk_add_f32 v[192:193], v[192:193], 1.0 op_sel_hi:[1,0]
	v_rcp_f32_e32 v174, v174
	v_rcp_f32_e32 v175, v175
	v_rcp_f32_e32 v188, v188
	v_rcp_f32_e32 v189, v189
	v_rcp_f32_e32 v190, v190
	v_rcp_f32_e32 v191, v191
	v_rcp_f32_e32 v192, v192
	v_rcp_f32_e32 v193, v193
	v_pk_mul_f32 v[132:133], v[132:133], v[174:175]
	v_pk_mul_f32 v[128:129], v[128:129], v[188:189]
	v_pk_mul_f32 v[134:135], v[134:135], v[190:191]
	v_pk_mul_f32 v[130:131], v[130:131], v[192:193]

; __device__ __forceinline__ unsigned pk2(float lo, float hi) { return pg8::cvt_pk_bf16(lo, hi); }
; __device__ __forceinline__ float gelu_tanh(float x) { const float u = 1.5957691216057308f * (x + 0.044715f * x * x * x); return x * sigmoidf_(u); }
;     __device__ __forceinline__ void operator()(const f32x4 (&acc)[2][2][4][2], const pg8::Unit& u, int wr, int wc, int fr, int fq) const {
;     ...
;             for (int m = 0; m < 4; ++m) {
;                 const int row = row0 + ai * 128 + m * 16;
;                 bf16_t* rowp = O + (size_t)row * ldc + col0;
;                 float s = 0.f, ss = 0.f;
; #pragma unroll
;                 for (int bj = 0; bj < 2; ++bj) {
;                     f32x4 v0 = acc[ai][bj][m][0] + bv[bj][0], v1 = acc[ai][bj][m][1] + bv[bj][1];
;                     if (do_gelu) {
; #pragma unroll
;                         for (int e = 0; e < 4; ++e) { v0[e] = gelu_tanh(v0[e]); v1[e] = gelu_tanh(v1[e]); }
;                     }
; #pragma unroll
;                     for (int e = 0; e < 4; ++e) { s += v0[e] + v1[e]; ss += v0[e] * v0[e] + v1[e] * v1[e]; }
;                     u32x4 w; w.x = pk2(v0[0], v0[1]); w.y = pk2(v0[2], v0[3]); w.z = pk2(v1[0], v1[1]); w.w = pk2(v1[2], v1[3]);
;                     *(u32x4*)(rowp + bj * 128) = w;
.LBB0_256:
	v_pk_add_f32 v[126:127], v[126:127], v[46:47]
	v_pk_add_f32 v[124:125], v[124:125], v[44:45]
	v_pk_add_f32 v[122:123], v[122:123], v[42:43]
	s_and_b64 vcc, exec, s[12:13]
	v_pk_add_f32 v[120:121], v[120:121], v[40:41]
	s_cbranch_vccnz .LBB0_258
	s_waitcnt lgkmcnt(0)
	v_pk_mul_f32 v[128:129], v[124:125], v[124:125]
	v_pk_mul_f32 v[130:131], v[120:121], v[120:121]
	v_pk_mul_f32 v[132:133], v[126:127], v[126:127]
	v_pk_mul_f32 v[134:135], v[122:123], v[122:123]
	v_pk_mul_f32 v[128:129], v[128:129], s[98:99] op_sel_hi:[1,0]
	v_pk_mul_f32 v[130:131], v[130:131], s[98:99] op_sel_hi:[1,0]
	v_pk_mul_f32 v[132:133], v[132:133], s[98:99] op_sel_hi:[1,0]
	v_pk_mul_f32 v[134:135], v[134:135], s[98:99] op_sel_hi:[1,0]
	v_pk_add_f32 v[128:129], v[128:129], s[100:101] op_sel_hi:[1,0]
	v_pk_add_f32 v[130:131], v[130:131], s[100:101] op_sel_hi:[1,0]
	v_pk_add_f32 v[132:133], v[132:133], s[100:101] op_sel_hi:[1,0]
	v_pk_add_f32 v[134:135], v[134:135], s[100:101] op_sel_hi:[1,0]
	v_pk_mul_f32 v[128:129], v[128:129], v[124:125]
	v_pk_mul_f32 v[130:131], v[130:131], v[120:121]
	v_pk_mul_f32 v[132:133], v[132:133], v[126:127]
	v_pk_mul_f32 v[134:135], v[134:135], v[122:123]
	v_exp_f32_e32 v128, v128
	v_exp_f32_e32 v129, v129
	v_exp_f32_e32 v130, v130
	v_exp_f32_e32 v131, v131
	v_exp_f32_e32 v132, v132
	v_exp_f32_e32 v133, v133
	v_exp_f32_e32 v134, v134
	v_exp_f32_e32 v135, v135
	v_pk_add_f32 v[128:129], v[128:129], 1.0 op_sel_hi:[1,0]
	v_pk_add_f32 v[130:131], v[130:131], 1.0 op_sel_hi:[1,0]
	v_pk_add_f32 v[132:133], v[132:133], 1.0 op_sel_hi:[1,0]
	v_pk_add_f32 v[134:135], v[134:135], 1.0 op_sel_hi:[1,0]
	v_rcp_f32_e32 v128, v128
	v_rcp_f32_e32 v129, v129
	v_rcp_f32_e32 v130, v130
	v_rcp_f32_e32 v131, v131
	v_rcp_f32_e32 v132, v132
	v_rcp_f32_e32 v133, v133
	v_rcp_f32_e32 v134, v134
	v_rcp_f32_e32 v135, v135
	v_pk_mul_f32 v[124:125], v[124:125], v[128:129]
	v_pk_mul_f32 v[120:121], v[120:121], v[130:131]
	v_pk_mul_f32 v[126:127], v[126:127], v[132:133]
	v_pk_mul_f32 v[122:123], v[122:123], v[134:135]
.LBB0_258:
	v_or_b32_e32 v128, 16, v136
	s_waitcnt lgkmcnt(0)
	v_mad_i64_i32 v[130:131], s[14:15], v128, s31, 0
	v_lshl_add_u64 v[130:131], v[130:131], 1, s[58:59]
	v_lshl_add_u64 v[130:131], v[156:157], 1, v[130:131]
	v_pk_add_f32 v[118:119], v[118:119], v[30:31]
	v_pk_add_f32 v[116:117], v[116:117], v[28:29]
	v_pk_add_f32 v[114:115], v[114:115], v[26:27]
	s_and_b64 vcc, exec, s[12:13]
	v_pk_add_f32 v[112:113], v[112:113], v[24:25]
	v_cvt_pk_bf16_f32 v132, v124, v125
	v_cvt_pk_bf16_f32 v133, v126, v127
	v_cvt_pk_bf16_f32 v134, v120, v121
	v_cvt_pk_bf16_f32 v135, v122, v123
	ds_bpermute_b32 v240, v238, v130
	ds_bpermute_b32 v241, v238, v131
	ds_bpermute_b32 v242, v238, v132
	ds_bpermute_b32 v243, v238, v133
	ds_bpermute_b32 v244, v238, v134
	ds_bpermute_b32 v245, v238, v135
	s_waitcnt lgkmcnt(6)
	global_store_dwordx4 v[248:249], v[250:253], off offset:256
	s_cbranch_vccnz .LBB0_260
	v_pk_mul_f32 v[132:133], v[116:117], v[116:117]
	v_pk_mul_f32 v[134:135], v[112:113], v[112:113]
	v_pk_mul_f32 v[138:139], v[118:119], v[118:119]
	v_pk_mul_f32 v[140:141], v[114:115], v[114:115]
	v_pk_mul_f32 v[132:133], v[132:133], s[98:99] op_sel_hi:[1,0]
	v_pk_mul_f32 v[134:135], v[134:135], s[98:99] op_sel_hi:[1,0]
	v_pk_mul_f32 v[138:139], v[138:139], s[98:99] op_sel_hi:[1,0]
	v_pk_mul_f32 v[140:141], v[140:141], s[98:99] op_sel_hi:[1,0]
	v_pk_add_f32 v[132:133], v[132:133], s[100:101] op_sel_hi:[1,0]
	v_pk_add_f32 v[134:135], v[134:135], s[100:101] op_sel_hi:[1,0]
	v_pk_add_f32 v[138:139], v[138:139], s[100:101] op_sel_hi:[1,0]
	v_pk_add_f32 v[140:141], v[140:141], s[100:101] op_sel_hi:[1,0]
	v_pk_mul_f32 v[132:133], v[132:133], v[116:117]
	v_pk_mul_f32 v[134:135], v[134:135], v[112:113]
	v_pk_mul_f32 v[138:139], v[138:139], v[118:119]
	v_pk_mul_f32 v[140:141], v[140:141], v[114:115]
	v_exp_f32_e32 v132, v132
	v_exp_f32_e32 v133, v133
	v_exp_f32_e32 v134, v134
	v_exp_f32_e32 v135, v135
	v_exp_f32_e32 v138, v138
	v_exp_f32_e32 v139, v139
	v_exp_f32_e32 v140, v140
	v_exp_f32_e32 v141, v141
	v_pk_add_f32 v[132:133], v[132:133], 1.0 op_sel_hi:[1,0]
	v_pk_add_f32 v[134:135], v[134:135], 1.0 op_sel_hi:[1,0]
	v_pk_add_f32 v[138:139], v[138:139], 1.0 op_sel_hi:[1,0]
	v_pk_add_f32 v[140:141], v[140:141], 1.0 op_sel_hi:[1,0]
	v_rcp_f32_e32 v132, v132
	v_rcp_f32_e32 v133, v133
	v_rcp_f32_e32 v134, v134
	v_rcp_f32_e32 v135, v135
	v_rcp_f32_e32 v138, v138
	v_rcp_f32_e32 v139, v139
	v_rcp_f32_e32 v140, v140
	v_rcp_f32_e32 v141, v141
	v_pk_mul_f32 v[116:117], v[116:117], v[132:133]
	v_pk_mul_f32 v[112:113], v[112:113], v[134:135]
	v_pk_mul_f32 v[118:119], v[118:119], v[138:139]
	v_pk_mul_f32 v[114:115], v[114:115], v[140:141]

; __device__ __forceinline__ unsigned pk2(float lo, float hi) { return pg8::cvt_pk_bf16(lo, hi); }
; __device__ __forceinline__ float gelu_tanh(float x) { const float u = 1.5957691216057308f * (x + 0.044715f * x * x * x); return x * sigmoidf_(u); }
;     __device__ __forceinline__ void operator()(const f32x4 (&acc)[2][2][4][2], const pg8::Unit& u, int wr, int wc, int fr, int fq) const {
;     ...
;             for (int m = 0; m < 4; ++m) {
;                 const int row = row0 + ai * 128 + m * 16;
;                 bf16_t* rowp = O + (size_t)row * ldc + col0;
;                 float s = 0.f, ss = 0.f;
; #pragma unroll
;                 for (int bj = 0; bj < 2; ++bj) {
;                     f32x4 v0 = acc[ai][bj][m][0] + bv[bj][0], v1 = acc[ai][bj][m][1] + bv[bj][1];
;                     if (do_gelu) {
; #pragma unroll
;                         for (int e = 0; e < 4; ++e) { v0[e] = gelu_tanh(v0[e]); v1[e] = gelu_tanh(v1[e]); }
;                     }
; #pragma unroll
;                     for (int e = 0; e < 4; ++e) { s += v0[e] + v1[e]; ss += v0[e] * v0[e] + v1[e] * v1[e]; }
;                     u32x4 w; w.x = pk2(v0[0], v0[1]); w.y = pk2(v0[2], v0[3]); w.z = pk2(v1[0], v1[1]); w.w = pk2(v1[2], v1[3]);
;                     *(u32x4*)(rowp + bj * 128) = w;
.LBB0_264:
	v_pk_add_f32 v[110:111], v[110:111], v[46:47]
	v_pk_add_f32 v[108:109], v[108:109], v[44:45]
	v_pk_add_f32 v[106:107], v[106:107], v[42:43]
	s_and_b64 vcc, exec, s[12:13]
	v_pk_add_f32 v[104:105], v[104:105], v[40:41]
	s_cbranch_vccnz .LBB0_266
	s_waitcnt lgkmcnt(0)
	v_pk_mul_f32 v[112:113], v[108:109], v[108:109]
	v_pk_mul_f32 v[114:115], v[104:105], v[104:105]
	v_pk_mul_f32 v[116:117], v[110:111], v[110:111]
	v_pk_mul_f32 v[118:119], v[106:107], v[106:107]
	v_pk_mul_f32 v[112:113], v[112:113], s[98:99] op_sel_hi:[1,0]
	v_pk_mul_f32 v[114:115], v[114:115], s[98:99] op_sel_hi:[1,0]
	v_pk_mul_f32 v[116:117], v[116:117], s[98:99] op_sel_hi:[1,0]
	v_pk_mul_f32 v[118:119], v[118:119], s[98:99] op_sel_hi:[1,0]
	v_pk_add_f32 v[112:113], v[112:113], s[100:101] op_sel_hi:[1,0]
	v_pk_add_f32 v[114:115], v[114:115], s[100:101] op_sel_hi:[1,0]
	v_pk_add_f32 v[116:117], v[116:117], s[100:101] op_sel_hi:[1,0]
	v_pk_add_f32 v[118:119], v[118:119], s[100:101] op_sel_hi:[1,0]
	v_pk_mul_f32 v[112:113], v[112:113], v[108:109]
	v_pk_mul_f32 v[114:115], v[114:115], v[104:105]
	v_pk_mul_f32 v[116:117], v[116:117], v[110:111]
	v_pk_mul_f32 v[118:119], v[118:119], v[106:107]
	v_exp_f32_e32 v112, v112
	v_exp_f32_e32 v113, v113
	v_exp_f32_e32 v114, v114
	v_exp_f32_e32 v115, v115
	v_exp_f32_e32 v116, v116
	v_exp_f32_e32 v117, v117
	v_exp_f32_e32 v118, v118
	v_exp_f32_e32 v119, v119
	v_pk_add_f32 v[112:113], v[112:113], 1.0 op_sel_hi:[1,0]
	v_pk_add_f32 v[114:115], v[114:115], 1.0 op_sel_hi:[1,0]
	v_pk_add_f32 v[116:117], v[116:117], 1.0 op_sel_hi:[1,0]
	v_pk_add_f32 v[118:119], v[118:119], 1.0 op_sel_hi:[1,0]
	v_rcp_f32_e32 v112, v112
	v_rcp_f32_e32 v113, v113
	v_rcp_f32_e32 v114, v114
	v_rcp_f32_e32 v115, v115
	v_rcp_f32_e32 v116, v116
	v_rcp_f32_e32 v117, v117
	v_rcp_f32_e32 v118, v118
	v_rcp_f32_e32 v119, v119
	v_pk_mul_f32 v[108:109], v[108:109], v[112:113]
	v_pk_mul_f32 v[104:105], v[104:105], v[114:115]
	v_pk_mul_f32 v[110:111], v[110:111], v[116:117]
	v_pk_mul_f32 v[106:107], v[106:107], v[118:119]
.LBB0_266:
	v_or_b32_e32 v112, 32, v136
	s_waitcnt lgkmcnt(0)
	v_mad_i64_i32 v[114:115], s[50:51], v112, s31, 0
	v_lshl_add_u64 v[114:115], v[114:115], 1, s[58:59]
	v_lshl_add_u64 v[114:115], v[156:157], 1, v[114:115]
	v_pk_add_f32 v[102:103], v[102:103], v[30:31]
	v_pk_add_f32 v[100:101], v[100:101], v[28:29]
	v_pk_add_f32 v[98:99], v[98:99], v[26:27]
	s_and_b64 vcc, exec, s[12:13]
	v_pk_add_f32 v[96:97], v[96:97], v[24:25]
	v_cvt_pk_bf16_f32 v116, v108, v109
	v_cvt_pk_bf16_f32 v117, v110, v111
	v_cvt_pk_bf16_f32 v118, v104, v105
	v_cvt_pk_bf16_f32 v119, v106, v107
	ds_bpermute_b32 v240, v238, v114
	ds_bpermute_b32 v241, v238, v115
	ds_bpermute_b32 v242, v238, v116
	ds_bpermute_b32 v243, v238, v117
	ds_bpermute_b32 v244, v238, v118
	ds_bpermute_b32 v245, v238, v119
	s_waitcnt lgkmcnt(6)
	global_store_dwordx4 v[248:249], v[250:253], off offset:256
	s_cbranch_vccnz .LBB0_268
	v_pk_mul_f32 v[116:117], v[100:101], v[100:101]
	v_pk_mul_f32 v[118:119], v[96:97], v[96:97]
	v_pk_mul_f32 v[120:121], v[102:103], v[102:103]
	v_pk_mul_f32 v[122:123], v[98:99], v[98:99]
	v_pk_mul_f32 v[116:117], v[116:117], s[98:99] op_sel_hi:[1,0]
	v_pk_mul_f32 v[118:119], v[118:119], s[98:99] op_sel_hi:[1,0]
	v_pk_mul_f32 v[120:121], v[120:121], s[98:99] op_sel_hi:[1,0]
	v_pk_mul_f32 v[122:123], v[122:123], s[98:99] op_sel_hi:[1,0]
	v_pk_add_f32 v[116:117], v[116:117], s[100:101] op_sel_hi:[1,0]
	v_pk_add_f32 v[118:119], v[118:119], s[100:101] op_sel_hi:[1,0]
	v_pk_add_f32 v[120:121], v[120:121], s[100:101] op_sel_hi:[1,0]
	v_pk_add_f32 v[122:123], v[122:123], s[100:101] op_sel_hi:[1,0]
	v_pk_mul_f32 v[116:117], v[116:117], v[100:101]
	v_pk_mul_f32 v[118:119], v[118:119], v[96:97]
	v_pk_mul_f32 v[120:121], v[120:121], v[102:103]
	v_pk_mul_f32 v[122:123], v[122:123], v[98:99]
	v_exp_f32_e32 v116, v116
	v_exp_f32_e32 v117, v117
	v_exp_f32_e32 v118, v118
	v_exp_f32_e32 v119, v119
	v_exp_f32_e32 v120, v120
	v_exp_f32_e32 v121, v121
	v_exp_f32_e32 v122, v122
	v_exp_f32_e32 v123, v123
	v_pk_add_f32 v[116:117], v[116:117], 1.0 op_sel_hi:[1,0]
	v_pk_add_f32 v[118:119], v[118:119], 1.0 op_sel_hi:[1,0]
	v_pk_add_f32 v[120:121], v[120:121], 1.0 op_sel_hi:[1,0]
	v_pk_add_f32 v[122:123], v[122:123], 1.0 op_sel_hi:[1,0]
	v_rcp_f32_e32 v116, v116
	v_rcp_f32_e32 v117, v117
	v_rcp_f32_e32 v118, v118
	v_rcp_f32_e32 v119, v119
	v_rcp_f32_e32 v120, v120
	v_rcp_f32_e32 v121, v121
	v_rcp_f32_e32 v122, v122
	v_rcp_f32_e32 v123, v123
	v_pk_mul_f32 v[100:101], v[100:101], v[116:117]
	v_pk_mul_f32 v[96:97], v[96:97], v[118:119]
	v_pk_mul_f32 v[102:103], v[102:103], v[120:121]
	v_pk_mul_f32 v[98:99], v[98:99], v[122:123]

; __device__ __forceinline__ unsigned pk2(float lo, float hi) { return pg8::cvt_pk_bf16(lo, hi); }
; __device__ __forceinline__ float gelu_tanh(float x) { const float u = 1.5957691216057308f * (x + 0.044715f * x * x * x); return x * sigmoidf_(u); }
;     __device__ __forceinline__ void operator()(const f32x4 (&acc)[2][2][4][2], const pg8::Unit& u, int wr, int wc, int fr, int fq) const {
;     ...
;             for (int m = 0; m < 4; ++m) {
;                 const int row = row0 + ai * 128 + m * 16;
;                 bf16_t* rowp = O + (size_t)row * ldc + col0;
;                 float s = 0.f, ss = 0.f;
; #pragma unroll
;                 for (int bj = 0; bj < 2; ++bj) {
;                     f32x4 v0 = acc[ai][bj][m][0] + bv[bj][0], v1 = acc[ai][bj][m][1] + bv[bj][1];
;                     if (do_gelu) {
; #pragma unroll
;                         for (int e = 0; e < 4; ++e) { v0[e] = gelu_tanh(v0[e]); v1[e] = gelu_tanh(v1[e]); }
;                     }
; #pragma unroll
;                     for (int e = 0; e < 4; ++e) { s += v0[e] + v1[e]; ss += v0[e] * v0[e] + v1[e] * v1[e]; }
;                     u32x4 w; w.x = pk2(v0[0], v0[1]); w.y = pk2(v0[2], v0[3]); w.z = pk2(v1[0], v1[1]); w.w = pk2(v1[2], v1[3]);
;                     *(u32x4*)(rowp + bj * 128) = w;
.LBB0_272:
	v_pk_add_f32 v[94:95], v[94:95], v[46:47]
	v_pk_add_f32 v[92:93], v[92:93], v[44:45]
	v_pk_add_f32 v[90:91], v[90:91], v[42:43]
	s_and_b64 vcc, exec, s[12:13]
	v_pk_add_f32 v[88:89], v[88:89], v[40:41]
	s_cbranch_vccnz .LBB0_274
	s_waitcnt lgkmcnt(0)
	v_pk_mul_f32 v[96:97], v[92:93], v[92:93]
	v_pk_mul_f32 v[98:99], v[88:89], v[88:89]
	v_pk_mul_f32 v[100:101], v[94:95], v[94:95]
	v_pk_mul_f32 v[102:103], v[90:91], v[90:91]
	v_pk_mul_f32 v[96:97], v[96:97], s[98:99] op_sel_hi:[1,0]
	v_pk_mul_f32 v[98:99], v[98:99], s[98:99] op_sel_hi:[1,0]
	v_pk_mul_f32 v[100:101], v[100:101], s[98:99] op_sel_hi:[1,0]
	v_pk_mul_f32 v[102:103], v[102:103], s[98:99] op_sel_hi:[1,0]
	v_pk_add_f32 v[96:97], v[96:97], s[100:101] op_sel_hi:[1,0]
	v_pk_add_f32 v[98:99], v[98:99], s[100:101] op_sel_hi:[1,0]
	v_pk_add_f32 v[100:101], v[100:101], s[100:101] op_sel_hi:[1,0]
	v_pk_add_f32 v[102:103], v[102:103], s[100:101] op_sel_hi:[1,0]
	v_pk_mul_f32 v[96:97], v[96:97], v[92:93]
	v_pk_mul_f32 v[98:99], v[98:99], v[88:89]
	v_pk_mul_f32 v[100:101], v[100:101], v[94:95]
	v_pk_mul_f32 v[102:103], v[102:103], v[90:91]
	v_exp_f32_e32 v96, v96
	v_exp_f32_e32 v97, v97
	v_exp_f32_e32 v98, v98
	v_exp_f32_e32 v99, v99
	v_exp_f32_e32 v100, v100
	v_exp_f32_e32 v101, v101
	v_exp_f32_e32 v102, v102
	v_exp_f32_e32 v103, v103
	v_pk_add_f32 v[96:97], v[96:97], 1.0 op_sel_hi:[1,0]
	v_pk_add_f32 v[98:99], v[98:99], 1.0 op_sel_hi:[1,0]
	v_pk_add_f32 v[100:101], v[100:101], 1.0 op_sel_hi:[1,0]
	v_pk_add_f32 v[102:103], v[102:103], 1.0 op_sel_hi:[1,0]
	v_rcp_f32_e32 v96, v96
	v_rcp_f32_e32 v97, v97
	v_rcp_f32_e32 v98, v98
	v_rcp_f32_e32 v99, v99
	v_rcp_f32_e32 v100, v100
	v_rcp_f32_e32 v101, v101
	v_rcp_f32_e32 v102, v102
	v_rcp_f32_e32 v103, v103
	v_pk_mul_f32 v[92:93], v[92:93], v[96:97]
	v_pk_mul_f32 v[88:89], v[88:89], v[98:99]
	v_pk_mul_f32 v[94:95], v[94:95], v[100:101]
	v_pk_mul_f32 v[90:91], v[90:91], v[102:103]
.LBB0_274:
	v_or_b32_e32 v96, 48, v136
	s_waitcnt lgkmcnt(0)
	v_mad_i64_i32 v[98:99], s[50:51], v96, s31, 0
	v_lshl_add_u64 v[98:99], v[98:99], 1, s[58:59]
	v_lshl_add_u64 v[98:99], v[156:157], 1, v[98:99]
	v_pk_add_f32 v[86:87], v[86:87], v[30:31]
	v_pk_add_f32 v[84:85], v[84:85], v[28:29]
	v_pk_add_f32 v[82:83], v[82:83], v[26:27]
	s_and_b64 vcc, exec, s[12:13]
	v_pk_add_f32 v[80:81], v[80:81], v[24:25]
	v_cvt_pk_bf16_f32 v100, v92, v93
	v_cvt_pk_bf16_f32 v101, v94, v95
	v_cvt_pk_bf16_f32 v102, v88, v89
	v_cvt_pk_bf16_f32 v103, v90, v91
	ds_bpermute_b32 v240, v238, v98
	ds_bpermute_b32 v241, v238, v99
	ds_bpermute_b32 v242, v238, v100
	ds_bpermute_b32 v243, v238, v101
	ds_bpermute_b32 v244, v238, v102
	ds_bpermute_b32 v245, v238, v103
	s_waitcnt lgkmcnt(6)
	global_store_dwordx4 v[248:249], v[250:253], off offset:256
	s_cbranch_vccnz .LBB0_276
	v_pk_mul_f32 v[100:101], v[84:85], v[84:85]
	v_pk_mul_f32 v[102:103], v[80:81], v[80:81]
	v_pk_mul_f32 v[104:105], v[86:87], v[86:87]
	v_pk_mul_f32 v[106:107], v[82:83], v[82:83]
	v_pk_mul_f32 v[100:101], v[100:101], s[98:99] op_sel_hi:[1,0]
	v_pk_mul_f32 v[102:103], v[102:103], s[98:99] op_sel_hi:[1,0]
	v_pk_mul_f32 v[104:105], v[104:105], s[98:99] op_sel_hi:[1,0]
	v_pk_mul_f32 v[106:107], v[106:107], s[98:99] op_sel_hi:[1,0]
	v_pk_add_f32 v[100:101], v[100:101], s[100:101] op_sel_hi:[1,0]
	v_pk_add_f32 v[102:103], v[102:103], s[100:101] op_sel_hi:[1,0]
	v_pk_add_f32 v[104:105], v[104:105], s[100:101] op_sel_hi:[1,0]
	v_pk_add_f32 v[106:107], v[106:107], s[100:101] op_sel_hi:[1,0]
	v_pk_mul_f32 v[100:101], v[100:101], v[84:85]
	v_pk_mul_f32 v[102:103], v[102:103], v[80:81]
	v_pk_mul_f32 v[104:105], v[104:105], v[86:87]
	v_pk_mul_f32 v[106:107], v[106:107], v[82:83]
	v_exp_f32_e32 v100, v100
	v_exp_f32_e32 v101, v101
	v_exp_f32_e32 v102, v102
	v_exp_f32_e32 v103, v103
	v_exp_f32_e32 v104, v104
	v_exp_f32_e32 v105, v105
	v_exp_f32_e32 v106, v106
	v_exp_f32_e32 v107, v107
	v_pk_add_f32 v[100:101], v[100:101], 1.0 op_sel_hi:[1,0]
	v_pk_add_f32 v[102:103], v[102:103], 1.0 op_sel_hi:[1,0]
	v_pk_add_f32 v[104:105], v[104:105], 1.0 op_sel_hi:[1,0]
	v_pk_add_f32 v[106:107], v[106:107], 1.0 op_sel_hi:[1,0]
	v_rcp_f32_e32 v100, v100
	v_rcp_f32_e32 v101, v101
	v_rcp_f32_e32 v102, v102
	v_rcp_f32_e32 v103, v103
	v_rcp_f32_e32 v104, v104
	v_rcp_f32_e32 v105, v105
	v_rcp_f32_e32 v106, v106
	v_rcp_f32_e32 v107, v107
	v_pk_mul_f32 v[84:85], v[84:85], v[100:101]
	v_pk_mul_f32 v[80:81], v[80:81], v[102:103]
	v_pk_mul_f32 v[86:87], v[86:87], v[104:105]
	v_pk_mul_f32 v[82:83], v[82:83], v[106:107]

; __device__ __forceinline__ unsigned pk2(float lo, float hi) { return pg8::cvt_pk_bf16(lo, hi); }
; __device__ __forceinline__ float gelu_tanh(float x) { const float u = 1.5957691216057308f * (x + 0.044715f * x * x * x); return x * sigmoidf_(u); }
;     __device__ __forceinline__ void operator()(const f32x4 (&acc)[2][2][4][2], const pg8::Unit& u, int wr, int wc, int fr, int fq) const {
;     ...
;             for (int m = 0; m < 4; ++m) {
;                 const int row = row0 + ai * 128 + m * 16;
;                 bf16_t* rowp = O + (size_t)row * ldc + col0;
;                 float s = 0.f, ss = 0.f;
; #pragma unroll
;                 for (int bj = 0; bj < 2; ++bj) {
;                     f32x4 v0 = acc[ai][bj][m][0] + bv[bj][0], v1 = acc[ai][bj][m][1] + bv[bj][1];
;                     if (do_gelu) {
; #pragma unroll
;                         for (int e = 0; e < 4; ++e) { v0[e] = gelu_tanh(v0[e]); v1[e] = gelu_tanh(v1[e]); }
;                     }
; #pragma unroll
;                     for (int e = 0; e < 4; ++e) { s += v0[e] + v1[e]; ss += v0[e] * v0[e] + v1[e] * v1[e]; }
;                     u32x4 w; w.x = pk2(v0[0], v0[1]); w.y = pk2(v0[2], v0[3]); w.z = pk2(v1[0], v1[1]); w.w = pk2(v1[2], v1[3]);
;                     *(u32x4*)(rowp + bj * 128) = w;
.LBB0_280:
	v_pk_add_f32 v[78:79], v[78:79], v[46:47]
	v_pk_add_f32 v[76:77], v[76:77], v[44:45]
	v_pk_add_f32 v[74:75], v[74:75], v[42:43]
	s_and_b64 vcc, exec, s[12:13]
	v_pk_add_f32 v[72:73], v[72:73], v[40:41]
	s_cbranch_vccnz .LBB0_282
	s_waitcnt lgkmcnt(0)
	v_pk_mul_f32 v[80:81], v[76:77], v[76:77]
	v_pk_mul_f32 v[82:83], v[72:73], v[72:73]
	v_pk_mul_f32 v[84:85], v[78:79], v[78:79]
	v_pk_mul_f32 v[86:87], v[74:75], v[74:75]
	v_pk_mul_f32 v[80:81], v[80:81], s[98:99] op_sel_hi:[1,0]
	v_pk_mul_f32 v[82:83], v[82:83], s[98:99] op_sel_hi:[1,0]
	v_pk_mul_f32 v[84:85], v[84:85], s[98:99] op_sel_hi:[1,0]
	v_pk_mul_f32 v[86:87], v[86:87], s[98:99] op_sel_hi:[1,0]
	v_pk_add_f32 v[80:81], v[80:81], s[100:101] op_sel_hi:[1,0]
	v_pk_add_f32 v[82:83], v[82:83], s[100:101] op_sel_hi:[1,0]
	v_pk_add_f32 v[84:85], v[84:85], s[100:101] op_sel_hi:[1,0]
	v_pk_add_f32 v[86:87], v[86:87], s[100:101] op_sel_hi:[1,0]
	v_pk_mul_f32 v[80:81], v[80:81], v[76:77]
	v_pk_mul_f32 v[82:83], v[82:83], v[72:73]
	v_pk_mul_f32 v[84:85], v[84:85], v[78:79]
	v_pk_mul_f32 v[86:87], v[86:87], v[74:75]
	v_exp_f32_e32 v80, v80
	v_exp_f32_e32 v81, v81
	v_exp_f32_e32 v82, v82
	v_exp_f32_e32 v83, v83
	v_exp_f32_e32 v84, v84
	v_exp_f32_e32 v85, v85
	v_exp_f32_e32 v86, v86
	v_exp_f32_e32 v87, v87
	v_pk_add_f32 v[80:81], v[80:81], 1.0 op_sel_hi:[1,0]
	v_pk_add_f32 v[82:83], v[82:83], 1.0 op_sel_hi:[1,0]
	v_pk_add_f32 v[84:85], v[84:85], 1.0 op_sel_hi:[1,0]
	v_pk_add_f32 v[86:87], v[86:87], 1.0 op_sel_hi:[1,0]
	v_rcp_f32_e32 v80, v80
	v_rcp_f32_e32 v81, v81
	v_rcp_f32_e32 v82, v82
	v_rcp_f32_e32 v83, v83
	v_rcp_f32_e32 v84, v84
	v_rcp_f32_e32 v85, v85
	v_rcp_f32_e32 v86, v86
	v_rcp_f32_e32 v87, v87
	v_pk_mul_f32 v[76:77], v[76:77], v[80:81]
	v_pk_mul_f32 v[72:73], v[72:73], v[82:83]
	v_pk_mul_f32 v[78:79], v[78:79], v[84:85]
	v_pk_mul_f32 v[74:75], v[74:75], v[86:87]
.LBB0_282:
	v_add_u32_e32 v80, 0x80, v136
	s_waitcnt lgkmcnt(0)
	v_mad_i64_i32 v[82:83], s[50:51], v80, s31, 0
	v_lshl_add_u64 v[82:83], v[82:83], 1, s[58:59]
	v_lshl_add_u64 v[82:83], v[156:157], 1, v[82:83]
	v_pk_add_f32 v[70:71], v[70:71], v[30:31]
	v_pk_add_f32 v[68:69], v[68:69], v[28:29]
	v_pk_add_f32 v[66:67], v[66:67], v[26:27]
	s_and_b64 vcc, exec, s[12:13]
	v_pk_add_f32 v[64:65], v[64:65], v[24:25]
	v_cvt_pk_bf16_f32 v84, v76, v77
	v_cvt_pk_bf16_f32 v85, v78, v79
	v_cvt_pk_bf16_f32 v86, v72, v73
	v_cvt_pk_bf16_f32 v87, v74, v75
	ds_bpermute_b32 v240, v238, v82
	ds_bpermute_b32 v241, v238, v83
	ds_bpermute_b32 v242, v238, v84
	ds_bpermute_b32 v243, v238, v85
	ds_bpermute_b32 v244, v238, v86
	ds_bpermute_b32 v245, v238, v87
	s_waitcnt lgkmcnt(6)
	global_store_dwordx4 v[248:249], v[250:253], off offset:256
	s_cbranch_vccnz .LBB0_284
	v_pk_mul_f32 v[84:85], v[68:69], v[68:69]
	v_pk_mul_f32 v[86:87], v[64:65], v[64:65]
	v_pk_mul_f32 v[88:89], v[70:71], v[70:71]
	v_pk_mul_f32 v[90:91], v[66:67], v[66:67]
	v_pk_mul_f32 v[84:85], v[84:85], s[98:99] op_sel_hi:[1,0]
	v_pk_mul_f32 v[86:87], v[86:87], s[98:99] op_sel_hi:[1,0]
	v_pk_mul_f32 v[88:89], v[88:89], s[98:99] op_sel_hi:[1,0]
	v_pk_mul_f32 v[90:91], v[90:91], s[98:99] op_sel_hi:[1,0]
	v_pk_add_f32 v[84:85], v[84:85], s[100:101] op_sel_hi:[1,0]
	v_pk_add_f32 v[86:87], v[86:87], s[100:101] op_sel_hi:[1,0]
	v_pk_add_f32 v[88:89], v[88:89], s[100:101] op_sel_hi:[1,0]
	v_pk_add_f32 v[90:91], v[90:91], s[100:101] op_sel_hi:[1,0]
	v_pk_mul_f32 v[84:85], v[84:85], v[68:69]
	v_pk_mul_f32 v[86:87], v[86:87], v[64:65]
	v_pk_mul_f32 v[88:89], v[88:89], v[70:71]
	v_pk_mul_f32 v[90:91], v[90:91], v[66:67]
	v_exp_f32_e32 v84, v84
	v_exp_f32_e32 v85, v85
	v_exp_f32_e32 v86, v86
	v_exp_f32_e32 v87, v87
	v_exp_f32_e32 v88, v88
	v_exp_f32_e32 v89, v89
	v_exp_f32_e32 v90, v90
	v_exp_f32_e32 v91, v91
	v_pk_add_f32 v[84:85], v[84:85], 1.0 op_sel_hi:[1,0]
	v_pk_add_f32 v[86:87], v[86:87], 1.0 op_sel_hi:[1,0]
	v_pk_add_f32 v[88:89], v[88:89], 1.0 op_sel_hi:[1,0]
	v_pk_add_f32 v[90:91], v[90:91], 1.0 op_sel_hi:[1,0]
	v_rcp_f32_e32 v84, v84
	v_rcp_f32_e32 v85, v85
	v_rcp_f32_e32 v86, v86
	v_rcp_f32_e32 v87, v87
	v_rcp_f32_e32 v88, v88
	v_rcp_f32_e32 v89, v89
	v_rcp_f32_e32 v90, v90
	v_rcp_f32_e32 v91, v91
	v_pk_mul_f32 v[68:69], v[68:69], v[84:85]
	v_pk_mul_f32 v[64:65], v[64:65], v[86:87]
	v_pk_mul_f32 v[70:71], v[70:71], v[88:89]
	v_pk_mul_f32 v[66:67], v[66:67], v[90:91]

; __device__ __forceinline__ unsigned pk2(float lo, float hi) { return pg8::cvt_pk_bf16(lo, hi); }
; __device__ __forceinline__ float gelu_tanh(float x) { const float u = 1.5957691216057308f * (x + 0.044715f * x * x * x); return x * sigmoidf_(u); }
;     __device__ __forceinline__ void operator()(const f32x4 (&acc)[2][2][4][2], const pg8::Unit& u, int wr, int wc, int fr, int fq) const {
;     ...
;             for (int m = 0; m < 4; ++m) {
;                 const int row = row0 + ai * 128 + m * 16;
;                 bf16_t* rowp = O + (size_t)row * ldc + col0;
;                 float s = 0.f, ss = 0.f;
; #pragma unroll
;                 for (int bj = 0; bj < 2; ++bj) {
;                     f32x4 v0 = acc[ai][bj][m][0] + bv[bj][0], v1 = acc[ai][bj][m][1] + bv[bj][1];
;                     if (do_gelu) {
; #pragma unroll
;                         for (int e = 0; e < 4; ++e) { v0[e] = gelu_tanh(v0[e]); v1[e] = gelu_tanh(v1[e]); }
;                     }
; #pragma unroll
;                     for (int e = 0; e < 4; ++e) { s += v0[e] + v1[e]; ss += v0[e] * v0[e] + v1[e] * v1[e]; }
;                     u32x4 w; w.x = pk2(v0[0], v0[1]); w.y = pk2(v0[2], v0[3]); w.z = pk2(v1[0], v1[1]); w.w = pk2(v1[2], v1[3]);
;                     *(u32x4*)(rowp + bj * 128) = w;
.LBB0_288:
	v_pk_add_f32 v[62:63], v[62:63], v[46:47]
	v_pk_add_f32 v[60:61], v[60:61], v[44:45]
	v_pk_add_f32 v[58:59], v[58:59], v[42:43]
	s_and_b64 vcc, exec, s[12:13]
	v_pk_add_f32 v[56:57], v[56:57], v[40:41]
	s_cbranch_vccnz .LBB0_290
	s_waitcnt lgkmcnt(0)
	v_pk_mul_f32 v[64:65], v[60:61], v[60:61]
	v_pk_mul_f32 v[66:67], v[56:57], v[56:57]
	v_pk_mul_f32 v[68:69], v[62:63], v[62:63]
	v_pk_mul_f32 v[70:71], v[58:59], v[58:59]
	v_pk_mul_f32 v[64:65], v[64:65], s[98:99] op_sel_hi:[1,0]
	v_pk_mul_f32 v[66:67], v[66:67], s[98:99] op_sel_hi:[1,0]
	v_pk_mul_f32 v[68:69], v[68:69], s[98:99] op_sel_hi:[1,0]
	v_pk_mul_f32 v[70:71], v[70:71], s[98:99] op_sel_hi:[1,0]
	v_pk_add_f32 v[64:65], v[64:65], s[100:101] op_sel_hi:[1,0]
	v_pk_add_f32 v[66:67], v[66:67], s[100:101] op_sel_hi:[1,0]
	v_pk_add_f32 v[68:69], v[68:69], s[100:101] op_sel_hi:[1,0]
	v_pk_add_f32 v[70:71], v[70:71], s[100:101] op_sel_hi:[1,0]
	v_pk_mul_f32 v[64:65], v[64:65], v[60:61]
	v_pk_mul_f32 v[66:67], v[66:67], v[56:57]
	v_pk_mul_f32 v[68:69], v[68:69], v[62:63]
	v_pk_mul_f32 v[70:71], v[70:71], v[58:59]
	v_exp_f32_e32 v64, v64
	v_exp_f32_e32 v65, v65
	v_exp_f32_e32 v66, v66
	v_exp_f32_e32 v67, v67
	v_exp_f32_e32 v68, v68
	v_exp_f32_e32 v69, v69
	v_exp_f32_e32 v70, v70
	v_exp_f32_e32 v71, v71
	v_pk_add_f32 v[64:65], v[64:65], 1.0 op_sel_hi:[1,0]
	v_pk_add_f32 v[66:67], v[66:67], 1.0 op_sel_hi:[1,0]
	v_pk_add_f32 v[68:69], v[68:69], 1.0 op_sel_hi:[1,0]
	v_pk_add_f32 v[70:71], v[70:71], 1.0 op_sel_hi:[1,0]
	v_rcp_f32_e32 v64, v64
	v_rcp_f32_e32 v65, v65
	v_rcp_f32_e32 v66, v66
	v_rcp_f32_e32 v67, v67
	v_rcp_f32_e32 v68, v68
	v_rcp_f32_e32 v69, v69
	v_rcp_f32_e32 v70, v70
	v_rcp_f32_e32 v71, v71
	v_pk_mul_f32 v[60:61], v[60:61], v[64:65]
	v_pk_mul_f32 v[56:57], v[56:57], v[66:67]
	v_pk_mul_f32 v[62:63], v[62:63], v[68:69]
	v_pk_mul_f32 v[58:59], v[58:59], v[70:71]
.LBB0_290:
	v_add_u32_e32 v64, 0x90, v136
	s_waitcnt lgkmcnt(0)
	v_mad_i64_i32 v[66:67], s[50:51], v64, s31, 0
	v_lshl_add_u64 v[66:67], v[66:67], 1, s[58:59]
	v_lshl_add_u64 v[66:67], v[156:157], 1, v[66:67]
	v_pk_add_f32 v[54:55], v[54:55], v[30:31]
	v_pk_add_f32 v[52:53], v[52:53], v[28:29]
	v_pk_add_f32 v[50:51], v[50:51], v[26:27]
	s_and_b64 vcc, exec, s[12:13]
	v_pk_add_f32 v[48:49], v[48:49], v[24:25]
	v_cvt_pk_bf16_f32 v68, v60, v61
	v_cvt_pk_bf16_f32 v69, v62, v63
	v_cvt_pk_bf16_f32 v70, v56, v57
	v_cvt_pk_bf16_f32 v71, v58, v59
	ds_bpermute_b32 v240, v238, v66
	ds_bpermute_b32 v241, v238, v67
	ds_bpermute_b32 v242, v238, v68
	ds_bpermute_b32 v243, v238, v69
	ds_bpermute_b32 v244, v238, v70
	ds_bpermute_b32 v245, v238, v71
	s_waitcnt lgkmcnt(6)
	global_store_dwordx4 v[248:249], v[250:253], off offset:256
	s_cbranch_vccnz .LBB0_292
	v_pk_mul_f32 v[68:69], v[52:53], v[52:53]
	v_pk_mul_f32 v[70:71], v[48:49], v[48:49]
	v_pk_mul_f32 v[72:73], v[54:55], v[54:55]
	v_pk_mul_f32 v[74:75], v[50:51], v[50:51]
	v_pk_mul_f32 v[68:69], v[68:69], s[98:99] op_sel_hi:[1,0]
	v_pk_mul_f32 v[70:71], v[70:71], s[98:99] op_sel_hi:[1,0]
	v_pk_mul_f32 v[72:73], v[72:73], s[98:99] op_sel_hi:[1,0]
	v_pk_mul_f32 v[74:75], v[74:75], s[98:99] op_sel_hi:[1,0]
	v_pk_add_f32 v[68:69], v[68:69], s[100:101] op_sel_hi:[1,0]
	v_pk_add_f32 v[70:71], v[70:71], s[100:101] op_sel_hi:[1,0]
	v_pk_add_f32 v[72:73], v[72:73], s[100:101] op_sel_hi:[1,0]
	v_pk_add_f32 v[74:75], v[74:75], s[100:101] op_sel_hi:[1,0]
	v_pk_mul_f32 v[68:69], v[68:69], v[52:53]
	v_pk_mul_f32 v[70:71], v[70:71], v[48:49]
	v_pk_mul_f32 v[72:73], v[72:73], v[54:55]
	v_pk_mul_f32 v[74:75], v[74:75], v[50:51]
	v_exp_f32_e32 v68, v68
	v_exp_f32_e32 v69, v69
	v_exp_f32_e32 v70, v70
	v_exp_f32_e32 v71, v71
	v_exp_f32_e32 v72, v72
	v_exp_f32_e32 v73, v73
	v_exp_f32_e32 v74, v74
	v_exp_f32_e32 v75, v75
	v_pk_add_f32 v[68:69], v[68:69], 1.0 op_sel_hi:[1,0]
	v_pk_add_f32 v[70:71], v[70:71], 1.0 op_sel_hi:[1,0]
	v_pk_add_f32 v[72:73], v[72:73], 1.0 op_sel_hi:[1,0]
	v_pk_add_f32 v[74:75], v[74:75], 1.0 op_sel_hi:[1,0]
	v_rcp_f32_e32 v68, v68
	v_rcp_f32_e32 v69, v69
	v_rcp_f32_e32 v70, v70
	v_rcp_f32_e32 v71, v71
	v_rcp_f32_e32 v72, v72
	v_rcp_f32_e32 v73, v73
	v_rcp_f32_e32 v74, v74
	v_rcp_f32_e32 v75, v75
	v_pk_mul_f32 v[52:53], v[52:53], v[68:69]
	v_pk_mul_f32 v[48:49], v[48:49], v[70:71]
	v_pk_mul_f32 v[54:55], v[54:55], v[72:73]
	v_pk_mul_f32 v[50:51], v[50:51], v[74:75]

; __device__ __forceinline__ unsigned pk2(float lo, float hi) { return pg8::cvt_pk_bf16(lo, hi); }
; __device__ __forceinline__ float gelu_tanh(float x) { const float u = 1.5957691216057308f * (x + 0.044715f * x * x * x); return x * sigmoidf_(u); }
;     __device__ __forceinline__ void operator()(const f32x4 (&acc)[2][2][4][2], const pg8::Unit& u, int wr, int wc, int fr, int fq) const {
;     ...
;             for (int m = 0; m < 4; ++m) {
;                 const int row = row0 + ai * 128 + m * 16;
;                 bf16_t* rowp = O + (size_t)row * ldc + col0;
;                 float s = 0.f, ss = 0.f;
; #pragma unroll
;                 for (int bj = 0; bj < 2; ++bj) {
;                     f32x4 v0 = acc[ai][bj][m][0] + bv[bj][0], v1 = acc[ai][bj][m][1] + bv[bj][1];
;                     if (do_gelu) {
; #pragma unroll
;                         for (int e = 0; e < 4; ++e) { v0[e] = gelu_tanh(v0[e]); v1[e] = gelu_tanh(v1[e]); }
;                     }
; #pragma unroll
;                     for (int e = 0; e < 4; ++e) { s += v0[e] + v1[e]; ss += v0[e] * v0[e] + v1[e] * v1[e]; }
;                     u32x4 w; w.x = pk2(v0[0], v0[1]); w.y = pk2(v0[2], v0[3]); w.z = pk2(v1[0], v1[1]); w.w = pk2(v1[2], v1[3]);
;                     *(u32x4*)(rowp + bj * 128) = w;
.LBB0_296:
	v_pk_add_f32 v[38:39], v[38:39], v[46:47]
	v_pk_add_f32 v[36:37], v[36:37], v[44:45]
	v_pk_add_f32 v[34:35], v[34:35], v[42:43]
	s_and_b64 vcc, exec, s[12:13]
	v_pk_add_f32 v[32:33], v[32:33], v[40:41]
	s_cbranch_vccnz .LBB0_298
	s_waitcnt lgkmcnt(0)
	v_pk_mul_f32 v[48:49], v[36:37], v[36:37]
	v_pk_mul_f32 v[50:51], v[32:33], v[32:33]
	v_pk_mul_f32 v[52:53], v[38:39], v[38:39]
	v_pk_mul_f32 v[54:55], v[34:35], v[34:35]
	v_pk_mul_f32 v[48:49], v[48:49], s[98:99] op_sel_hi:[1,0]
	v_pk_mul_f32 v[50:51], v[50:51], s[98:99] op_sel_hi:[1,0]
	v_pk_mul_f32 v[52:53], v[52:53], s[98:99] op_sel_hi:[1,0]
	v_pk_mul_f32 v[54:55], v[54:55], s[98:99] op_sel_hi:[1,0]
	v_pk_add_f32 v[48:49], v[48:49], s[100:101] op_sel_hi:[1,0]
	v_pk_add_f32 v[50:51], v[50:51], s[100:101] op_sel_hi:[1,0]
	v_pk_add_f32 v[52:53], v[52:53], s[100:101] op_sel_hi:[1,0]
	v_pk_add_f32 v[54:55], v[54:55], s[100:101] op_sel_hi:[1,0]
	v_pk_mul_f32 v[48:49], v[48:49], v[36:37]
	v_pk_mul_f32 v[50:51], v[50:51], v[32:33]
	v_pk_mul_f32 v[52:53], v[52:53], v[38:39]
	v_pk_mul_f32 v[54:55], v[54:55], v[34:35]
	v_exp_f32_e32 v48, v48
	v_exp_f32_e32 v49, v49
	v_exp_f32_e32 v50, v50
	v_exp_f32_e32 v51, v51
	v_exp_f32_e32 v52, v52
	v_exp_f32_e32 v53, v53
	v_exp_f32_e32 v54, v54
	v_exp_f32_e32 v55, v55
	v_pk_add_f32 v[48:49], v[48:49], 1.0 op_sel_hi:[1,0]
	v_pk_add_f32 v[50:51], v[50:51], 1.0 op_sel_hi:[1,0]
	v_pk_add_f32 v[52:53], v[52:53], 1.0 op_sel_hi:[1,0]
	v_pk_add_f32 v[54:55], v[54:55], 1.0 op_sel_hi:[1,0]
	v_rcp_f32_e32 v48, v48
	v_rcp_f32_e32 v49, v49
	v_rcp_f32_e32 v50, v50
	v_rcp_f32_e32 v51, v51
	v_rcp_f32_e32 v52, v52
	v_rcp_f32_e32 v53, v53
	v_rcp_f32_e32 v54, v54
	v_rcp_f32_e32 v55, v55
	v_pk_mul_f32 v[36:37], v[36:37], v[48:49]
	v_pk_mul_f32 v[32:33], v[32:33], v[50:51]
	v_pk_mul_f32 v[38:39], v[38:39], v[52:53]
	v_pk_mul_f32 v[34:35], v[34:35], v[54:55]
.LBB0_298:
	v_add_u32_e32 v48, 0xa0, v136
	s_waitcnt lgkmcnt(0)
	v_mad_i64_i32 v[50:51], s[50:51], v48, s31, 0
	v_lshl_add_u64 v[50:51], v[50:51], 1, s[58:59]
	v_lshl_add_u64 v[50:51], v[156:157], 1, v[50:51]
	v_pk_add_f32 v[22:23], v[22:23], v[30:31]
	v_pk_add_f32 v[20:21], v[20:21], v[28:29]
	v_pk_add_f32 v[18:19], v[18:19], v[26:27]
	s_and_b64 vcc, exec, s[12:13]
	v_pk_add_f32 v[16:17], v[16:17], v[24:25]
	v_cvt_pk_bf16_f32 v52, v36, v37
	v_cvt_pk_bf16_f32 v53, v38, v39
	v_cvt_pk_bf16_f32 v54, v32, v33
	v_cvt_pk_bf16_f32 v55, v34, v35
	ds_bpermute_b32 v240, v238, v50
	ds_bpermute_b32 v241, v238, v51
	ds_bpermute_b32 v242, v238, v52
	ds_bpermute_b32 v243, v238, v53
	ds_bpermute_b32 v244, v238, v54
	ds_bpermute_b32 v245, v238, v55
	s_waitcnt lgkmcnt(6)
	global_store_dwordx4 v[248:249], v[250:253], off offset:256
	s_cbranch_vccnz .LBB0_300
	v_pk_mul_f32 v[52:53], v[20:21], v[20:21]
	v_pk_mul_f32 v[54:55], v[16:17], v[16:17]
	v_pk_mul_f32 v[56:57], v[22:23], v[22:23]
	v_pk_mul_f32 v[58:59], v[18:19], v[18:19]
	v_pk_mul_f32 v[52:53], v[52:53], s[98:99] op_sel_hi:[1,0]
	v_pk_mul_f32 v[54:55], v[54:55], s[98:99] op_sel_hi:[1,0]
	v_pk_mul_f32 v[56:57], v[56:57], s[98:99] op_sel_hi:[1,0]
	v_pk_mul_f32 v[58:59], v[58:59], s[98:99] op_sel_hi:[1,0]
	v_pk_add_f32 v[52:53], v[52:53], s[100:101] op_sel_hi:[1,0]
	v_pk_add_f32 v[54:55], v[54:55], s[100:101] op_sel_hi:[1,0]
	v_pk_add_f32 v[56:57], v[56:57], s[100:101] op_sel_hi:[1,0]
	v_pk_add_f32 v[58:59], v[58:59], s[100:101] op_sel_hi:[1,0]
	v_pk_mul_f32 v[52:53], v[52:53], v[20:21]
	v_pk_mul_f32 v[54:55], v[54:55], v[16:17]
	v_pk_mul_f32 v[56:57], v[56:57], v[22:23]
	v_pk_mul_f32 v[58:59], v[58:59], v[18:19]
	v_exp_f32_e32 v52, v52
	v_exp_f32_e32 v53, v53
	v_exp_f32_e32 v54, v54
	v_exp_f32_e32 v55, v55
	v_exp_f32_e32 v56, v56
	v_exp_f32_e32 v57, v57
	v_exp_f32_e32 v58, v58
	v_exp_f32_e32 v59, v59
	v_pk_add_f32 v[52:53], v[52:53], 1.0 op_sel_hi:[1,0]
	v_pk_add_f32 v[54:55], v[54:55], 1.0 op_sel_hi:[1,0]
	v_pk_add_f32 v[56:57], v[56:57], 1.0 op_sel_hi:[1,0]
	v_pk_add_f32 v[58:59], v[58:59], 1.0 op_sel_hi:[1,0]
	v_rcp_f32_e32 v52, v52
	v_rcp_f32_e32 v53, v53
	v_rcp_f32_e32 v54, v54
	v_rcp_f32_e32 v55, v55
	v_rcp_f32_e32 v56, v56
	v_rcp_f32_e32 v57, v57
	v_rcp_f32_e32 v58, v58
	v_rcp_f32_e32 v59, v59
	v_pk_mul_f32 v[20:21], v[20:21], v[52:53]
	v_pk_mul_f32 v[16:17], v[16:17], v[54:55]
	v_pk_mul_f32 v[22:23], v[22:23], v[56:57]
	v_pk_mul_f32 v[18:19], v[18:19], v[58:59]

; __device__ __forceinline__ unsigned pk2(float lo, float hi) { return pg8::cvt_pk_bf16(lo, hi); }
; __device__ __forceinline__ float gelu_tanh(float x) { const float u = 1.5957691216057308f * (x + 0.044715f * x * x * x); return x * sigmoidf_(u); }
;     __device__ __forceinline__ void operator()(const f32x4 (&acc)[2][2][4][2], const pg8::Unit& u, int wr, int wc, int fr, int fq) const {
;     ...
;             for (int m = 0; m < 4; ++m) {
;                 const int row = row0 + ai * 128 + m * 16;
;                 bf16_t* rowp = O + (size_t)row * ldc + col0;
;                 float s = 0.f, ss = 0.f;
; #pragma unroll
;                 for (int bj = 0; bj < 2; ++bj) {
;                     f32x4 v0 = acc[ai][bj][m][0] + bv[bj][0], v1 = acc[ai][bj][m][1] + bv[bj][1];
;                     if (do_gelu) {
; #pragma unroll
;                         for (int e = 0; e < 4; ++e) { v0[e] = gelu_tanh(v0[e]); v1[e] = gelu_tanh(v1[e]); }
;                     }
; #pragma unroll
;                     for (int e = 0; e < 4; ++e) { s += v0[e] + v1[e]; ss += v0[e] * v0[e] + v1[e] * v1[e]; }
;                     u32x4 w; w.x = pk2(v0[0], v0[1]); w.y = pk2(v0[2], v0[3]); w.z = pk2(v1[0], v1[1]); w.w = pk2(v1[2], v1[3]);
;                     *(u32x4*)(rowp + bj * 128) = w;
.LBB0_304:
	v_pk_add_f32 v[14:15], v[14:15], v[46:47]
	v_pk_add_f32 v[12:13], v[12:13], v[44:45]
	v_pk_add_f32 v[10:11], v[10:11], v[42:43]
	s_and_b64 vcc, exec, s[12:13]
	v_pk_add_f32 v[8:9], v[8:9], v[40:41]
	s_cbranch_vccnz .LBB0_306
	s_waitcnt lgkmcnt(0)
	v_pk_mul_f32 v[16:17], v[12:13], v[12:13]
	v_pk_mul_f32 v[18:19], v[8:9], v[8:9]
	v_pk_mul_f32 v[20:21], v[14:15], v[14:15]
	v_pk_mul_f32 v[22:23], v[10:11], v[10:11]
	v_pk_mul_f32 v[16:17], v[16:17], s[98:99] op_sel_hi:[1,0]
	v_pk_mul_f32 v[18:19], v[18:19], s[98:99] op_sel_hi:[1,0]
	v_pk_mul_f32 v[20:21], v[20:21], s[98:99] op_sel_hi:[1,0]
	v_pk_mul_f32 v[22:23], v[22:23], s[98:99] op_sel_hi:[1,0]
	v_pk_add_f32 v[16:17], v[16:17], s[100:101] op_sel_hi:[1,0]
	v_pk_add_f32 v[18:19], v[18:19], s[100:101] op_sel_hi:[1,0]
	v_pk_add_f32 v[20:21], v[20:21], s[100:101] op_sel_hi:[1,0]
	v_pk_add_f32 v[22:23], v[22:23], s[100:101] op_sel_hi:[1,0]
	v_pk_mul_f32 v[16:17], v[16:17], v[12:13]
	v_pk_mul_f32 v[18:19], v[18:19], v[8:9]
	v_pk_mul_f32 v[20:21], v[20:21], v[14:15]
	v_pk_mul_f32 v[22:23], v[22:23], v[10:11]
	v_exp_f32_e32 v16, v16
	v_exp_f32_e32 v17, v17
	v_exp_f32_e32 v18, v18
	v_exp_f32_e32 v19, v19
	v_exp_f32_e32 v20, v20
	v_exp_f32_e32 v21, v21
	v_exp_f32_e32 v22, v22
	v_exp_f32_e32 v23, v23
	v_pk_add_f32 v[16:17], v[16:17], 1.0 op_sel_hi:[1,0]
	v_pk_add_f32 v[18:19], v[18:19], 1.0 op_sel_hi:[1,0]
	v_pk_add_f32 v[20:21], v[20:21], 1.0 op_sel_hi:[1,0]
	v_pk_add_f32 v[22:23], v[22:23], 1.0 op_sel_hi:[1,0]
	v_rcp_f32_e32 v16, v16
	v_rcp_f32_e32 v17, v17
	v_rcp_f32_e32 v18, v18
	v_rcp_f32_e32 v19, v19
	v_rcp_f32_e32 v20, v20
	v_rcp_f32_e32 v21, v21
	v_rcp_f32_e32 v22, v22
	v_rcp_f32_e32 v23, v23
	v_pk_mul_f32 v[12:13], v[12:13], v[16:17]
	v_pk_mul_f32 v[8:9], v[8:9], v[18:19]
	v_pk_mul_f32 v[14:15], v[14:15], v[20:21]
	v_pk_mul_f32 v[10:11], v[10:11], v[22:23]
.LBB0_306:
	v_add_u32_e32 v16, 0xb0, v136
	s_waitcnt lgkmcnt(0)
	v_mad_i64_i32 v[18:19], s[50:51], v16, s31, 0
	v_lshl_add_u64 v[18:19], v[18:19], 1, s[58:59]
	v_lshl_add_u64 v[18:19], v[156:157], 1, v[18:19]
	v_pk_add_f32 v[6:7], v[6:7], v[30:31]
	v_pk_add_f32 v[4:5], v[4:5], v[28:29]
	v_pk_add_f32 v[2:3], v[2:3], v[26:27]
	s_and_b64 vcc, exec, s[12:13]
	v_pk_add_f32 v[0:1], v[0:1], v[24:25]
	v_cvt_pk_bf16_f32 v20, v12, v13
	v_cvt_pk_bf16_f32 v21, v14, v15
	v_cvt_pk_bf16_f32 v22, v8, v9
	v_cvt_pk_bf16_f32 v23, v10, v11
	ds_bpermute_b32 v240, v238, v18
	ds_bpermute_b32 v241, v238, v19
	ds_bpermute_b32 v242, v238, v20
	ds_bpermute_b32 v243, v238, v21
	ds_bpermute_b32 v244, v238, v22
	ds_bpermute_b32 v245, v238, v23
	s_waitcnt lgkmcnt(6)
	global_store_dwordx4 v[248:249], v[250:253], off offset:256
	s_cbranch_vccnz .LBB0_308
	v_pk_mul_f32 v[20:21], v[4:5], v[4:5]
	v_pk_mul_f32 v[22:23], v[0:1], v[0:1]
	v_pk_mul_f32 v[24:25], v[6:7], v[6:7]
	v_pk_mul_f32 v[26:27], v[2:3], v[2:3]
	v_pk_mul_f32 v[20:21], v[20:21], s[98:99] op_sel_hi:[1,0]
	v_pk_mul_f32 v[22:23], v[22:23], s[98:99] op_sel_hi:[1,0]
	v_pk_mul_f32 v[24:25], v[24:25], s[98:99] op_sel_hi:[1,0]
	v_pk_mul_f32 v[26:27], v[26:27], s[98:99] op_sel_hi:[1,0]
	v_pk_add_f32 v[20:21], v[20:21], s[100:101] op_sel_hi:[1,0]
	v_pk_add_f32 v[22:23], v[22:23], s[100:101] op_sel_hi:[1,0]
	v_pk_add_f32 v[24:25], v[24:25], s[100:101] op_sel_hi:[1,0]
	v_pk_add_f32 v[26:27], v[26:27], s[100:101] op_sel_hi:[1,0]
	v_pk_mul_f32 v[20:21], v[20:21], v[4:5]
	v_pk_mul_f32 v[22:23], v[22:23], v[0:1]
	v_pk_mul_f32 v[24:25], v[24:25], v[6:7]
	v_pk_mul_f32 v[26:27], v[26:27], v[2:3]
	v_exp_f32_e32 v20, v20
	v_exp_f32_e32 v21, v21
	v_exp_f32_e32 v22, v22
	v_exp_f32_e32 v23, v23
	v_exp_f32_e32 v24, v24
	v_exp_f32_e32 v25, v25
	v_exp_f32_e32 v26, v26
	v_exp_f32_e32 v27, v27
	v_pk_add_f32 v[20:21], v[20:21], 1.0 op_sel_hi:[1,0]
	v_pk_add_f32 v[22:23], v[22:23], 1.0 op_sel_hi:[1,0]
	v_pk_add_f32 v[24:25], v[24:25], 1.0 op_sel_hi:[1,0]
	v_pk_add_f32 v[26:27], v[26:27], 1.0 op_sel_hi:[1,0]
	v_rcp_f32_e32 v20, v20
	v_rcp_f32_e32 v21, v21
	v_rcp_f32_e32 v22, v22
	v_rcp_f32_e32 v23, v23
	v_rcp_f32_e32 v24, v24
	v_rcp_f32_e32 v25, v25
	v_rcp_f32_e32 v26, v26
	v_rcp_f32_e32 v27, v27
	v_pk_mul_f32 v[4:5], v[4:5], v[20:21]
	v_pk_mul_f32 v[0:1], v[0:1], v[22:23]
	v_pk_mul_f32 v[6:7], v[6:7], v[24:25]
	v_pk_mul_f32 v[2:3], v[2:3], v[26:27]

; __global__ void __launch_bounds__(NTHR, 2) trunk_fwd(Params p) {
	.amdhsa_kernel _Z9trunk_fwd6Params
		.amdhsa_group_segment_fixed_size 0
		.amdhsa_private_segment_fixed_size 0
		.amdhsa_kernarg_size 496
		.amdhsa_user_sgpr_count 2
		.amdhsa_user_sgpr_dispatch_ptr 0
		.amdhsa_user_sgpr_queue_ptr 0
		.amdhsa_user_sgpr_kernarg_segment_ptr 1
		.amdhsa_user_sgpr_dispatch_id 0
		.amdhsa_user_sgpr_kernarg_preload_length 0
		.amdhsa_user_sgpr_kernarg_preload_offset 0
		.amdhsa_user_sgpr_private_segment_size 0
		.amdhsa_uses_dynamic_stack 0
		.amdhsa_enable_private_segment 0
		.amdhsa_system_sgpr_workgroup_id_x 1
		.amdhsa_system_sgpr_workgroup_id_y 0
		.amdhsa_system_sgpr_workgroup_id_z 0
		.amdhsa_system_sgpr_workgroup_info 0
		.amdhsa_system_vgpr_workitem_id 2
		.amdhsa_next_free_vgpr 256
		.amdhsa_next_free_sgpr 102
		.amdhsa_accum_offset 256
		.amdhsa_reserve_vcc 1
		.amdhsa_float_round_mode_32 0
		.amdhsa_float_round_mode_16_64 0
		.amdhsa_float_denorm_mode_32 3
		.amdhsa_float_denorm_mode_16_64 3
		.amdhsa_dx10_clamp 1
		.amdhsa_ieee_mode 1
		.amdhsa_fp16_overflow 0
		.amdhsa_tg_split 0
		.amdhsa_exception_fp_ieee_invalid_op 0
		.amdhsa_exception_fp_denorm_src 0
		.amdhsa_exception_fp_ieee_div_zero 0
		.amdhsa_exception_fp_ieee_overflow 0
		.amdhsa_exception_fp_ieee_underflow 0
		.amdhsa_exception_fp_ieee_inexact 0
		.amdhsa_exception_int_div_zero 0
	.end_amdhsa_kernel

; __global__ void __launch_bounds__(NTHR, 2) trunk_fwd(Params p) {
amdhsa.kernels:
  - .agpr_count:     0
    .args:
      - .offset:         0
        .size:           240
        .value_kind:     by_value
      - .offset:         240
        .size:           4
        .value_kind:     hidden_block_count_x
      - .offset:         244
        .size:           4
        .value_kind:     hidden_block_count_y
      - .offset:         248
        .size:           4
        .value_kind:     hidden_block_count_z
      - .offset:         252
        .size:           2
        .value_kind:     hidden_group_size_x
      - .offset:         254
        .size:           2
        .value_kind:     hidden_group_size_y
      - .offset:         256
        .size:           2
        .value_kind:     hidden_group_size_z
      - .offset:         258
        .size:           2
        .value_kind:     hidden_remainder_x
      - .offset:         260
        .size:           2
        .value_kind:     hidden_remainder_y
      - .offset:         262
        .size:           2
        .value_kind:     hidden_remainder_z
      - .offset:         280
        .size:           8
        .value_kind:     hidden_global_offset_x
      - .offset:         288
        .size:           8
        .value_kind:     hidden_global_offset_y
      - .offset:         296
        .size:           8
        .value_kind:     hidden_global_offset_z
      - .offset:         304
        .size:           2
        .value_kind:     hidden_grid_dims
      - .offset:         328
        .size:           8
        .value_kind:     hidden_multigrid_sync_arg
      - .offset:         360
        .size:           4
        .value_kind:     hidden_dynamic_lds_size
    .group_segment_fixed_size: 0
    .kernarg_segment_align: 8
    .kernarg_segment_size: 496
    .language:       OpenCL C
    .language_version:
      - 2
      - 0
    .max_flat_workgroup_size: 512
    .name:           _Z9trunk_fwd6Params
    .private_segment_fixed_size: 0
    .sgpr_count:     108
    .sgpr_spill_count: 22
    .symbol:         _Z9trunk_fwd6Params.kd
    .uniform_work_group_size: 1
    .uses_dynamic_stack: false
    .vgpr_count:     256
    .vgpr_spill_count: 0
    .wavefront_size: 64
